# FF-IN act stores made write-through (sc1) to shorten the L2 write-back at the grid barrier
# speedup vs baseline: 1.0323x; 1.0022x over previous
;     __device__ __forceinline__ void operator()(const f32x4 (&acc)[2][2][4][2], const Unit& u, int wr, int wc, int fr, int fq) const {
;     ...
;             for (int m = 0; m < 4; ++m) {
;                 const int row = row0 + ai * HALF + m * 16; const float rs = rsv[m];
;                 const f32x4 ca = acc[ai][0][m][0] * rs, cb_ = acc[ai][0][m][1] * rs;
;                 f32x4 aa = w2a * ca + ba, ab = w2b * cb_ + bb;
; #pragma unroll
;                 for (int c = 0; c < 4; ++c) { aa[c] = __builtin_fmaf(w1a[c], dpp_shr1(ca[c]), aa[c]); ab[c] = __builtin_fmaf(w1b[c], dpp_shr1(cb_[c]), ab[c]);
;                     aa[c] = __builtin_fmaf(w0a[c], dpp_shr2(ca[c]), aa[c]); ab[c] = __builtin_fmaf(w0b[c], dpp_shr2(cb_[c]), ab[c]); }
;                 if (m == 0) {
;                     if (ai == 1 || wr == 1) { const int sw = ((ai == 1 && wr == 0) ? 4 : 0) + wc, sai = (ai == 1 && wr == 1) ? 1 : 0;
;                         const PG8_LAS f32x4* xp = (const PG8_LAS f32x4*)(X + ((sw * 2 + sai) * 2) * 32 + fq * 8); const f32x4 h0a = xp[0], h0b = xp[1], h1a = xp[8], h1b = xp[9];
;                         aa += w1a * (h1a * m0) + w0a * (h0a * m0 + h1a * m1); ab += w1b * (h1b * m0) + w0b * (h0b * m0 + h1b * m1); }
;                 } else {
; #pragma unroll
;                     for (int c = 0; c < 4; ++c) { aa[c] = __builtin_fmaf(w1a[c], dpp_shl15(pa[c]), aa[c]); ab[c] = __builtin_fmaf(w1b[c], dpp_shl15(pb[c]), ab[c]);
;                         aa[c] = __builtin_fmaf(w0a[c], dpp_shl14(pa[c]), aa[c]); ab[c] = __builtin_fmaf(w0b[c], dpp_shl14(pb[c]), ab[c]); }
;                 }
;                 const f32x4 ga = acc[ai][1][m][0] * rs, gb = acc[ai][1][m][1] * rs;
;                 f32x4 ea = aa * -1.4426950408889634f, eb = ab * -1.4426950408889634f;
; #pragma unroll
;                 for (int c = 0; c < 4; ++c) { ea[c] = __builtin_amdgcn_exp2f(ea[c]); eb[c] = __builtin_amdgcn_exp2f(eb[c]); }
;                 ea = ea + 1.0f; eb = eb + 1.0f;
; #pragma unroll
;                 for (int c = 0; c < 4; ++c) { ea[c] = __builtin_amdgcn_rcpf(ea[c]); eb[c] = __builtin_amdgcn_rcpf(eb[c]); }
;                 const f32x4 oa = (aa * ga) * ea, ob = (ab * gb) * eb;
;                 u32x4 w; w.x = cvt_pk_bf16(oa[0], oa[1]); w.y = cvt_pk_bf16(oa[2], oa[3]); w.z = cvt_pk_bf16(ob[0], ob[1]); w.w = cvt_pk_bf16(ob[2], ob[3]);
;                 *(u32x4*)(act + (size_t)row * FF + col) = w;
.Lffin_nopark:
	s_or_b64 exec, exec, s[46:47]
	v_pk_mul_f32 v[244:245], v[236:237], s[92:93] op_sel_hi:[1,0]
	v_pk_mul_f32 v[246:247], v[238:239], s[92:93] op_sel_hi:[1,0]
	v_pk_mul_f32 v[248:249], v[240:241], s[92:93] op_sel_hi:[1,0]
	v_pk_mul_f32 v[250:251], v[242:243], s[92:93] op_sel_hi:[1,0]
	v_exp_f32_e32 v244, v244
	v_exp_f32_e32 v245, v245
	v_exp_f32_e32 v246, v246
	v_exp_f32_e32 v247, v247
	v_exp_f32_e32 v248, v248
	v_exp_f32_e32 v249, v249
	v_exp_f32_e32 v250, v250
	v_exp_f32_e32 v251, v251
	v_pk_mul_f32 v[236:237], v[236:237], v[150:151]
	v_pk_mul_f32 v[238:239], v[238:239], v[152:153]
	v_pk_mul_f32 v[240:241], v[240:241], v[146:147]
	v_pk_mul_f32 v[242:243], v[242:243], v[148:149]
	v_pk_add_f32 v[244:245], v[244:245], 1.0 op_sel_hi:[1,0]
	v_pk_add_f32 v[246:247], v[246:247], 1.0 op_sel_hi:[1,0]
	v_pk_add_f32 v[248:249], v[248:249], 1.0 op_sel_hi:[1,0]
	v_pk_add_f32 v[250:251], v[250:251], 1.0 op_sel_hi:[1,0]
	v_rcp_f32_e32 v244, v244
	v_rcp_f32_e32 v245, v245
	v_rcp_f32_e32 v246, v246
	v_rcp_f32_e32 v247, v247
	v_rcp_f32_e32 v248, v248
	v_rcp_f32_e32 v249, v249
	v_rcp_f32_e32 v250, v250
	v_rcp_f32_e32 v251, v251
	s_nop 0
	v_pk_mul_f32 v[236:237], v[236:237], v[244:245]
	v_pk_mul_f32 v[238:239], v[238:239], v[246:247]
	v_pk_mul_f32 v[240:241], v[240:241], v[248:249]
	v_pk_mul_f32 v[242:243], v[242:243], v[250:251]
	v_cvt_pk_bf16_f32 v216, v236, v237
	v_cvt_pk_bf16_f32 v217, v238, v239
	v_cvt_pk_bf16_f32 v218, v240, v241
	v_cvt_pk_bf16_f32 v219, v242, v243
	global_store_dwordx4 v[220:221], v[216:219], off sc1
	v_lshl_add_u64 v[220:221], v[220:221], 0, s[100:101]
	v_pk_mul_f32 v[142:143], v[142:143], v[164:165] op_sel_hi:[1,0]
	v_pk_mul_f32 v[144:145], v[144:145], v[164:165] op_sel_hi:[1,0]
	v_pk_mul_f32 v[138:139], v[138:139], v[164:165] op_sel_hi:[1,0]
	v_pk_mul_f32 v[140:141], v[140:141], v[164:165] op_sel_hi:[1,0]
	v_pk_fma_f32 v[236:237], v[122:123], v[142:143], v[130:131]
	v_pk_fma_f32 v[238:239], v[124:125], v[144:145], v[132:133]
	v_pk_fma_f32 v[240:241], v[126:127], v[138:139], v[134:135]
	v_pk_fma_f32 v[242:243], v[128:129], v[140:141], v[136:137]
	v_pk_mul_f32 v[102:103], v[102:103], v[164:165] op_sel_hi:[1,0]
	v_pk_mul_f32 v[104:105], v[104:105], v[164:165] op_sel_hi:[1,0]
	v_pk_mul_f32 v[98:99], v[98:99], v[164:165] op_sel_hi:[1,0]
	v_pk_mul_f32 v[100:101], v[100:101], v[164:165] op_sel_hi:[1,0]
	v_fmac_f32_dpp v236, v142, v114 row_shr:1 row_mask:0xf bank_mask:0xf bound_ctrl:1
	v_fmac_f32_dpp v237, v143, v115 row_shr:1 row_mask:0xf bank_mask:0xf bound_ctrl:1
	v_fmac_f32_dpp v238, v144, v116 row_shr:1 row_mask:0xf bank_mask:0xf bound_ctrl:1
	v_fmac_f32_dpp v239, v145, v117 row_shr:1 row_mask:0xf bank_mask:0xf bound_ctrl:1
	v_fmac_f32_dpp v240, v138, v118 row_shr:1 row_mask:0xf bank_mask:0xf bound_ctrl:1
	v_fmac_f32_dpp v241, v139, v119 row_shr:1 row_mask:0xf bank_mask:0xf bound_ctrl:1
	v_fmac_f32_dpp v242, v140, v120 row_shr:1 row_mask:0xf bank_mask:0xf bound_ctrl:1
	v_fmac_f32_dpp v243, v141, v121 row_shr:1 row_mask:0xf bank_mask:0xf bound_ctrl:1
	v_fmac_f32_dpp v236, v142, v106 row_shr:2 row_mask:0xf bank_mask:0xf bound_ctrl:1
	v_fmac_f32_dpp v237, v143, v107 row_shr:2 row_mask:0xf bank_mask:0xf bound_ctrl:1
	v_fmac_f32_dpp v238, v144, v108 row_shr:2 row_mask:0xf bank_mask:0xf bound_ctrl:1
	v_fmac_f32_dpp v239, v145, v109 row_shr:2 row_mask:0xf bank_mask:0xf bound_ctrl:1
	v_fmac_f32_dpp v240, v138, v110 row_shr:2 row_mask:0xf bank_mask:0xf bound_ctrl:1
	v_fmac_f32_dpp v241, v139, v111 row_shr:2 row_mask:0xf bank_mask:0xf bound_ctrl:1
	v_fmac_f32_dpp v242, v140, v112 row_shr:2 row_mask:0xf bank_mask:0xf bound_ctrl:1
	v_fmac_f32_dpp v243, v141, v113 row_shr:2 row_mask:0xf bank_mask:0xf bound_ctrl:1
	v_fmac_f32_dpp v236, v158, v114 row_shl:15 row_mask:0xf bank_mask:0xf bound_ctrl:1
	v_fmac_f32_dpp v237, v159, v115 row_shl:15 row_mask:0xf bank_mask:0xf bound_ctrl:1
	v_fmac_f32_dpp v238, v160, v116 row_shl:15 row_mask:0xf bank_mask:0xf bound_ctrl:1
	v_fmac_f32_dpp v239, v161, v117 row_shl:15 row_mask:0xf bank_mask:0xf bound_ctrl:1
	v_fmac_f32_dpp v240, v154, v118 row_shl:15 row_mask:0xf bank_mask:0xf bound_ctrl:1
	v_fmac_f32_dpp v241, v155, v119 row_shl:15 row_mask:0xf bank_mask:0xf bound_ctrl:1
	v_fmac_f32_dpp v242, v156, v120 row_shl:15 row_mask:0xf bank_mask:0xf bound_ctrl:1
	v_fmac_f32_dpp v243, v157, v121 row_shl:15 row_mask:0xf bank_mask:0xf bound_ctrl:1
	v_fmac_f32_dpp v236, v158, v106 row_shl:14 row_mask:0xf bank_mask:0xf bound_ctrl:1
	v_fmac_f32_dpp v237, v159, v107 row_shl:14 row_mask:0xf bank_mask:0xf bound_ctrl:1
	v_fmac_f32_dpp v238, v160, v108 row_shl:14 row_mask:0xf bank_mask:0xf bound_ctrl:1
	v_fmac_f32_dpp v239, v161, v109 row_shl:14 row_mask:0xf bank_mask:0xf bound_ctrl:1
	v_fmac_f32_dpp v240, v154, v110 row_shl:14 row_mask:0xf bank_mask:0xf bound_ctrl:1
	v_fmac_f32_dpp v241, v155, v111 row_shl:14 row_mask:0xf bank_mask:0xf bound_ctrl:1
	v_fmac_f32_dpp v242, v156, v112 row_shl:14 row_mask:0xf bank_mask:0xf bound_ctrl:1
	v_fmac_f32_dpp v243, v157, v113 row_shl:14 row_mask:0xf bank_mask:0xf bound_ctrl:1
	v_pk_mul_f32 v[244:245], v[236:237], s[92:93] op_sel_hi:[1,0]
	v_pk_mul_f32 v[246:247], v[238:239], s[92:93] op_sel_hi:[1,0]
	v_pk_mul_f32 v[248:249], v[240:241], s[92:93] op_sel_hi:[1,0]
	v_pk_mul_f32 v[250:251], v[242:243], s[92:93] op_sel_hi:[1,0]
	v_exp_f32_e32 v244, v244
	v_exp_f32_e32 v245, v245
	v_exp_f32_e32 v246, v246
	v_exp_f32_e32 v247, v247
	v_exp_f32_e32 v248, v248
	v_exp_f32_e32 v249, v249
	v_exp_f32_e32 v250, v250
	v_exp_f32_e32 v251, v251
	v_pk_mul_f32 v[236:237], v[236:237], v[102:103]
	v_pk_mul_f32 v[238:239], v[238:239], v[104:105]
	v_pk_mul_f32 v[240:241], v[240:241], v[98:99]
;     __device__ __forceinline__ void operator()(const f32x4 (&acc)[2][2][4][2], const Unit& u, int wr, int wc, int fr, int fq) const {
;     ...
;             for (int m = 0; m < 4; ++m) {
;                 const int row = row0 + ai * HALF + m * 16; const float rs = rsv[m];
;                 const f32x4 ca = acc[ai][0][m][0] * rs, cb_ = acc[ai][0][m][1] * rs;
;                 f32x4 aa = w2a * ca + ba, ab = w2b * cb_ + bb;
; #pragma unroll
;                 for (int c = 0; c < 4; ++c) { aa[c] = __builtin_fmaf(w1a[c], dpp_shr1(ca[c]), aa[c]); ab[c] = __builtin_fmaf(w1b[c], dpp_shr1(cb_[c]), ab[c]);
;                     aa[c] = __builtin_fmaf(w0a[c], dpp_shr2(ca[c]), aa[c]); ab[c] = __builtin_fmaf(w0b[c], dpp_shr2(cb_[c]), ab[c]); }
;                 if (m == 0) {
;                     if (ai == 1 || wr == 1) { const int sw = ((ai == 1 && wr == 0) ? 4 : 0) + wc, sai = (ai == 1 && wr == 1) ? 1 : 0;
;                         const PG8_LAS f32x4* xp = (const PG8_LAS f32x4*)(X + ((sw * 2 + sai) * 2) * 32 + fq * 8); const f32x4 h0a = xp[0], h0b = xp[1], h1a = xp[8], h1b = xp[9];
;                         aa += w1a * (h1a * m0) + w0a * (h0a * m0 + h1a * m1); ab += w1b * (h1b * m0) + w0b * (h0b * m0 + h1b * m1); }
;                 } else {
; #pragma unroll
;                     for (int c = 0; c < 4; ++c) { aa[c] = __builtin_fmaf(w1a[c], dpp_shl15(pa[c]), aa[c]); ab[c] = __builtin_fmaf(w1b[c], dpp_shl15(pb[c]), ab[c]);
;                         aa[c] = __builtin_fmaf(w0a[c], dpp_shl14(pa[c]), aa[c]); ab[c] = __builtin_fmaf(w0b[c], dpp_shl14(pb[c]), ab[c]); }
;                 }
;                 const f32x4 ga = acc[ai][1][m][0] * rs, gb = acc[ai][1][m][1] * rs;
;                 f32x4 ea = aa * -1.4426950408889634f, eb = ab * -1.4426950408889634f;
; #pragma unroll
;                 for (int c = 0; c < 4; ++c) { ea[c] = __builtin_amdgcn_exp2f(ea[c]); eb[c] = __builtin_amdgcn_exp2f(eb[c]); }
;                 ea = ea + 1.0f; eb = eb + 1.0f;
; #pragma unroll
;                 for (int c = 0; c < 4; ++c) { ea[c] = __builtin_amdgcn_rcpf(ea[c]); eb[c] = __builtin_amdgcn_rcpf(eb[c]); }
;                 const f32x4 oa = (aa * ga) * ea, ob = (ab * gb) * eb;
;                 u32x4 w; w.x = cvt_pk_bf16(oa[0], oa[1]); w.y = cvt_pk_bf16(oa[2], oa[3]); w.z = cvt_pk_bf16(ob[0], ob[1]); w.w = cvt_pk_bf16(ob[2], ob[3]);
;                 *(u32x4*)(act + (size_t)row * FF + col) = w;
	v_pk_mul_f32 v[242:243], v[242:243], v[100:101]
	v_pk_add_f32 v[244:245], v[244:245], 1.0 op_sel_hi:[1,0]
	v_pk_add_f32 v[246:247], v[246:247], 1.0 op_sel_hi:[1,0]
	v_pk_add_f32 v[248:249], v[248:249], 1.0 op_sel_hi:[1,0]
	v_pk_add_f32 v[250:251], v[250:251], 1.0 op_sel_hi:[1,0]
	v_rcp_f32_e32 v244, v244
	v_rcp_f32_e32 v245, v245
	v_rcp_f32_e32 v246, v246
	v_rcp_f32_e32 v247, v247
	v_rcp_f32_e32 v248, v248
	v_rcp_f32_e32 v249, v249
	v_rcp_f32_e32 v250, v250
	v_rcp_f32_e32 v251, v251
	s_nop 0
	v_pk_mul_f32 v[236:237], v[236:237], v[244:245]
	v_pk_mul_f32 v[238:239], v[238:239], v[246:247]
	v_pk_mul_f32 v[240:241], v[240:241], v[248:249]
	v_pk_mul_f32 v[242:243], v[242:243], v[250:251]
	v_cvt_pk_bf16_f32 v216, v236, v237
	v_cvt_pk_bf16_f32 v217, v238, v239
	v_cvt_pk_bf16_f32 v218, v240, v241
	v_cvt_pk_bf16_f32 v219, v242, v243
	global_store_dwordx4 v[220:221], v[216:219], off sc1
	v_lshl_add_u64 v[220:221], v[220:221], 0, s[100:101]
	v_pk_mul_f32 v[94:95], v[94:95], v[166:167] op_sel_hi:[1,0]
	v_pk_mul_f32 v[96:97], v[96:97], v[166:167] op_sel_hi:[1,0]
	v_pk_mul_f32 v[90:91], v[90:91], v[166:167] op_sel_hi:[1,0]
	v_pk_mul_f32 v[92:93], v[92:93], v[166:167] op_sel_hi:[1,0]
	v_pk_fma_f32 v[236:237], v[122:123], v[94:95], v[130:131]
	v_pk_fma_f32 v[238:239], v[124:125], v[96:97], v[132:133]
	v_pk_fma_f32 v[240:241], v[126:127], v[90:91], v[134:135]
	v_pk_fma_f32 v[242:243], v[128:129], v[92:93], v[136:137]
	v_pk_mul_f32 v[86:87], v[86:87], v[166:167] op_sel_hi:[1,0]
	v_pk_mul_f32 v[88:89], v[88:89], v[166:167] op_sel_hi:[1,0]
	v_pk_mul_f32 v[82:83], v[82:83], v[166:167] op_sel_hi:[1,0]
	v_pk_mul_f32 v[84:85], v[84:85], v[166:167] op_sel_hi:[1,0]
	v_fmac_f32_dpp v236, v94, v114 row_shr:1 row_mask:0xf bank_mask:0xf bound_ctrl:1
	v_fmac_f32_dpp v237, v95, v115 row_shr:1 row_mask:0xf bank_mask:0xf bound_ctrl:1
	v_fmac_f32_dpp v238, v96, v116 row_shr:1 row_mask:0xf bank_mask:0xf bound_ctrl:1
	v_fmac_f32_dpp v239, v97, v117 row_shr:1 row_mask:0xf bank_mask:0xf bound_ctrl:1
	v_fmac_f32_dpp v240, v90, v118 row_shr:1 row_mask:0xf bank_mask:0xf bound_ctrl:1
	v_fmac_f32_dpp v241, v91, v119 row_shr:1 row_mask:0xf bank_mask:0xf bound_ctrl:1
	v_fmac_f32_dpp v242, v92, v120 row_shr:1 row_mask:0xf bank_mask:0xf bound_ctrl:1
	v_fmac_f32_dpp v243, v93, v121 row_shr:1 row_mask:0xf bank_mask:0xf bound_ctrl:1
	v_fmac_f32_dpp v236, v94, v106 row_shr:2 row_mask:0xf bank_mask:0xf bound_ctrl:1
	v_fmac_f32_dpp v237, v95, v107 row_shr:2 row_mask:0xf bank_mask:0xf bound_ctrl:1
	v_fmac_f32_dpp v238, v96, v108 row_shr:2 row_mask:0xf bank_mask:0xf bound_ctrl:1
	v_fmac_f32_dpp v239, v97, v109 row_shr:2 row_mask:0xf bank_mask:0xf bound_ctrl:1
	v_fmac_f32_dpp v240, v90, v110 row_shr:2 row_mask:0xf bank_mask:0xf bound_ctrl:1
	v_fmac_f32_dpp v241, v91, v111 row_shr:2 row_mask:0xf bank_mask:0xf bound_ctrl:1
	v_fmac_f32_dpp v242, v92, v112 row_shr:2 row_mask:0xf bank_mask:0xf bound_ctrl:1
	v_fmac_f32_dpp v243, v93, v113 row_shr:2 row_mask:0xf bank_mask:0xf bound_ctrl:1
	v_fmac_f32_dpp v236, v142, v114 row_shl:15 row_mask:0xf bank_mask:0xf bound_ctrl:1
	v_fmac_f32_dpp v237, v143, v115 row_shl:15 row_mask:0xf bank_mask:0xf bound_ctrl:1
	v_fmac_f32_dpp v238, v144, v116 row_shl:15 row_mask:0xf bank_mask:0xf bound_ctrl:1
	v_fmac_f32_dpp v239, v145, v117 row_shl:15 row_mask:0xf bank_mask:0xf bound_ctrl:1
	v_fmac_f32_dpp v240, v138, v118 row_shl:15 row_mask:0xf bank_mask:0xf bound_ctrl:1
	v_fmac_f32_dpp v241, v139, v119 row_shl:15 row_mask:0xf bank_mask:0xf bound_ctrl:1
	v_fmac_f32_dpp v242, v140, v120 row_shl:15 row_mask:0xf bank_mask:0xf bound_ctrl:1
	v_fmac_f32_dpp v243, v141, v121 row_shl:15 row_mask:0xf bank_mask:0xf bound_ctrl:1
	v_fmac_f32_dpp v236, v142, v106 row_shl:14 row_mask:0xf bank_mask:0xf bound_ctrl:1
	v_fmac_f32_dpp v237, v143, v107 row_shl:14 row_mask:0xf bank_mask:0xf bound_ctrl:1
	v_fmac_f32_dpp v238, v144, v108 row_shl:14 row_mask:0xf bank_mask:0xf bound_ctrl:1
	v_fmac_f32_dpp v239, v145, v109 row_shl:14 row_mask:0xf bank_mask:0xf bound_ctrl:1
	v_fmac_f32_dpp v240, v138, v110 row_shl:14 row_mask:0xf bank_mask:0xf bound_ctrl:1
	v_fmac_f32_dpp v241, v139, v111 row_shl:14 row_mask:0xf bank_mask:0xf bound_ctrl:1
	v_fmac_f32_dpp v242, v140, v112 row_shl:14 row_mask:0xf bank_mask:0xf bound_ctrl:1
	v_fmac_f32_dpp v243, v141, v113 row_shl:14 row_mask:0xf bank_mask:0xf bound_ctrl:1
	v_pk_mul_f32 v[244:245], v[236:237], s[92:93] op_sel_hi:[1,0]
	v_pk_mul_f32 v[246:247], v[238:239], s[92:93] op_sel_hi:[1,0]
	v_pk_mul_f32 v[248:249], v[240:241], s[92:93] op_sel_hi:[1,0]
	v_pk_mul_f32 v[250:251], v[242:243], s[92:93] op_sel_hi:[1,0]
	v_exp_f32_e32 v244, v244
	v_exp_f32_e32 v245, v245
	v_exp_f32_e32 v246, v246
	v_exp_f32_e32 v247, v247
	v_exp_f32_e32 v248, v248
	v_exp_f32_e32 v249, v249
	v_exp_f32_e32 v250, v250
	v_exp_f32_e32 v251, v251
	v_pk_mul_f32 v[236:237], v[236:237], v[86:87]
	v_pk_mul_f32 v[238:239], v[238:239], v[88:89]
	v_pk_mul_f32 v[240:241], v[240:241], v[82:83]
	v_pk_mul_f32 v[242:243], v[242:243], v[84:85]
	v_pk_add_f32 v[244:245], v[244:245], 1.0 op_sel_hi:[1,0]
	v_pk_add_f32 v[246:247], v[246:247], 1.0 op_sel_hi:[1,0]
	v_pk_add_f32 v[248:249], v[248:249], 1.0 op_sel_hi:[1,0]
	v_pk_add_f32 v[250:251], v[250:251], 1.0 op_sel_hi:[1,0]
	v_rcp_f32_e32 v244, v244
	v_rcp_f32_e32 v245, v245
	v_rcp_f32_e32 v246, v246
	v_rcp_f32_e32 v247, v247
	v_rcp_f32_e32 v248, v248
	v_rcp_f32_e32 v249, v249
	v_rcp_f32_e32 v250, v250
	v_rcp_f32_e32 v251, v251
	s_nop 0
	v_pk_mul_f32 v[236:237], v[236:237], v[244:245]
	v_pk_mul_f32 v[238:239], v[238:239], v[246:247]
	v_pk_mul_f32 v[240:241], v[240:241], v[248:249]
	v_pk_mul_f32 v[242:243], v[242:243], v[250:251]
	v_cvt_pk_bf16_f32 v216, v236, v237
;     __device__ __forceinline__ void operator()(const f32x4 (&acc)[2][2][4][2], const Unit& u, int wr, int wc, int fr, int fq) const {
;     ...
;             for (int m = 0; m < 4; ++m) {
;                 const int row = row0 + ai * HALF + m * 16; const float rs = rsv[m];
;                 const f32x4 ca = acc[ai][0][m][0] * rs, cb_ = acc[ai][0][m][1] * rs;
;                 f32x4 aa = w2a * ca + ba, ab = w2b * cb_ + bb;
; #pragma unroll
;                 for (int c = 0; c < 4; ++c) { aa[c] = __builtin_fmaf(w1a[c], dpp_shr1(ca[c]), aa[c]); ab[c] = __builtin_fmaf(w1b[c], dpp_shr1(cb_[c]), ab[c]);
;                     aa[c] = __builtin_fmaf(w0a[c], dpp_shr2(ca[c]), aa[c]); ab[c] = __builtin_fmaf(w0b[c], dpp_shr2(cb_[c]), ab[c]); }
;                 if (m == 0) {
;                     if (ai == 1 || wr == 1) { const int sw = ((ai == 1 && wr == 0) ? 4 : 0) + wc, sai = (ai == 1 && wr == 1) ? 1 : 0;
;                         const PG8_LAS f32x4* xp = (const PG8_LAS f32x4*)(X + ((sw * 2 + sai) * 2) * 32 + fq * 8); const f32x4 h0a = xp[0], h0b = xp[1], h1a = xp[8], h1b = xp[9];
;                         aa += w1a * (h1a * m0) + w0a * (h0a * m0 + h1a * m1); ab += w1b * (h1b * m0) + w0b * (h0b * m0 + h1b * m1); }
;                 } else {
; #pragma unroll
;                     for (int c = 0; c < 4; ++c) { aa[c] = __builtin_fmaf(w1a[c], dpp_shl15(pa[c]), aa[c]); ab[c] = __builtin_fmaf(w1b[c], dpp_shl15(pb[c]), ab[c]);
;                         aa[c] = __builtin_fmaf(w0a[c], dpp_shl14(pa[c]), aa[c]); ab[c] = __builtin_fmaf(w0b[c], dpp_shl14(pb[c]), ab[c]); }
;                 }
;                 const f32x4 ga = acc[ai][1][m][0] * rs, gb = acc[ai][1][m][1] * rs;
;                 f32x4 ea = aa * -1.4426950408889634f, eb = ab * -1.4426950408889634f;
; #pragma unroll
;                 for (int c = 0; c < 4; ++c) { ea[c] = __builtin_amdgcn_exp2f(ea[c]); eb[c] = __builtin_amdgcn_exp2f(eb[c]); }
;                 ea = ea + 1.0f; eb = eb + 1.0f;
; #pragma unroll
;                 for (int c = 0; c < 4; ++c) { ea[c] = __builtin_amdgcn_rcpf(ea[c]); eb[c] = __builtin_amdgcn_rcpf(eb[c]); }
;                 const f32x4 oa = (aa * ga) * ea, ob = (ab * gb) * eb;
;                 u32x4 w; w.x = cvt_pk_bf16(oa[0], oa[1]); w.y = cvt_pk_bf16(oa[2], oa[3]); w.z = cvt_pk_bf16(ob[0], ob[1]); w.w = cvt_pk_bf16(ob[2], ob[3]);
;                 *(u32x4*)(act + (size_t)row * FF + col) = w;
	v_cvt_pk_bf16_f32 v217, v238, v239
	v_cvt_pk_bf16_f32 v218, v240, v241
	v_cvt_pk_bf16_f32 v219, v242, v243
	global_store_dwordx4 v[220:221], v[216:219], off sc1
	v_lshl_add_u64 v[220:221], v[220:221], 0, s[100:101]
	v_pk_fma_f32 v[236:237], v[122:123], v[78:79], v[130:131]
	v_pk_fma_f32 v[238:239], v[124:125], v[80:81], v[132:133]
	v_pk_fma_f32 v[240:241], v[126:127], v[74:75], v[134:135]
	v_pk_fma_f32 v[242:243], v[128:129], v[76:77], v[136:137]
	v_pk_mul_f32 v[70:71], v[70:71], v[168:169] op_sel_hi:[1,0]
	v_pk_mul_f32 v[72:73], v[72:73], v[168:169] op_sel_hi:[1,0]
	v_pk_mul_f32 v[66:67], v[66:67], v[168:169] op_sel_hi:[1,0]
	v_pk_mul_f32 v[68:69], v[68:69], v[168:169] op_sel_hi:[1,0]
	v_fmac_f32_dpp v236, v78, v114 row_shr:1 row_mask:0xf bank_mask:0xf bound_ctrl:1
	v_fmac_f32_dpp v237, v79, v115 row_shr:1 row_mask:0xf bank_mask:0xf bound_ctrl:1
	v_fmac_f32_dpp v238, v80, v116 row_shr:1 row_mask:0xf bank_mask:0xf bound_ctrl:1
	v_fmac_f32_dpp v239, v81, v117 row_shr:1 row_mask:0xf bank_mask:0xf bound_ctrl:1
	v_fmac_f32_dpp v240, v74, v118 row_shr:1 row_mask:0xf bank_mask:0xf bound_ctrl:1
	v_fmac_f32_dpp v241, v75, v119 row_shr:1 row_mask:0xf bank_mask:0xf bound_ctrl:1
	v_fmac_f32_dpp v242, v76, v120 row_shr:1 row_mask:0xf bank_mask:0xf bound_ctrl:1
	v_fmac_f32_dpp v243, v77, v121 row_shr:1 row_mask:0xf bank_mask:0xf bound_ctrl:1
	v_fmac_f32_dpp v236, v78, v106 row_shr:2 row_mask:0xf bank_mask:0xf bound_ctrl:1
	v_fmac_f32_dpp v237, v79, v107 row_shr:2 row_mask:0xf bank_mask:0xf bound_ctrl:1
	v_fmac_f32_dpp v238, v80, v108 row_shr:2 row_mask:0xf bank_mask:0xf bound_ctrl:1
	v_fmac_f32_dpp v239, v81, v109 row_shr:2 row_mask:0xf bank_mask:0xf bound_ctrl:1
	v_fmac_f32_dpp v240, v74, v110 row_shr:2 row_mask:0xf bank_mask:0xf bound_ctrl:1
	v_fmac_f32_dpp v241, v75, v111 row_shr:2 row_mask:0xf bank_mask:0xf bound_ctrl:1
	v_fmac_f32_dpp v242, v76, v112 row_shr:2 row_mask:0xf bank_mask:0xf bound_ctrl:1
	v_fmac_f32_dpp v243, v77, v113 row_shr:2 row_mask:0xf bank_mask:0xf bound_ctrl:1
	v_fmac_f32_dpp v236, v94, v114 row_shl:15 row_mask:0xf bank_mask:0xf bound_ctrl:1
	v_fmac_f32_dpp v237, v95, v115 row_shl:15 row_mask:0xf bank_mask:0xf bound_ctrl:1
	v_fmac_f32_dpp v238, v96, v116 row_shl:15 row_mask:0xf bank_mask:0xf bound_ctrl:1
	v_fmac_f32_dpp v239, v97, v117 row_shl:15 row_mask:0xf bank_mask:0xf bound_ctrl:1
	v_fmac_f32_dpp v240, v90, v118 row_shl:15 row_mask:0xf bank_mask:0xf bound_ctrl:1
	v_fmac_f32_dpp v241, v91, v119 row_shl:15 row_mask:0xf bank_mask:0xf bound_ctrl:1
	v_fmac_f32_dpp v242, v92, v120 row_shl:15 row_mask:0xf bank_mask:0xf bound_ctrl:1
	v_fmac_f32_dpp v243, v93, v121 row_shl:15 row_mask:0xf bank_mask:0xf bound_ctrl:1
	v_fmac_f32_dpp v236, v94, v106 row_shl:14 row_mask:0xf bank_mask:0xf bound_ctrl:1
	v_fmac_f32_dpp v237, v95, v107 row_shl:14 row_mask:0xf bank_mask:0xf bound_ctrl:1
	v_fmac_f32_dpp v238, v96, v108 row_shl:14 row_mask:0xf bank_mask:0xf bound_ctrl:1
	v_fmac_f32_dpp v239, v97, v109 row_shl:14 row_mask:0xf bank_mask:0xf bound_ctrl:1
	v_fmac_f32_dpp v240, v90, v110 row_shl:14 row_mask:0xf bank_mask:0xf bound_ctrl:1
	v_fmac_f32_dpp v241, v91, v111 row_shl:14 row_mask:0xf bank_mask:0xf bound_ctrl:1
	v_fmac_f32_dpp v242, v92, v112 row_shl:14 row_mask:0xf bank_mask:0xf bound_ctrl:1
	v_fmac_f32_dpp v243, v93, v113 row_shl:14 row_mask:0xf bank_mask:0xf bound_ctrl:1
	v_pk_mul_f32 v[244:245], v[236:237], s[92:93] op_sel_hi:[1,0]
	v_pk_mul_f32 v[246:247], v[238:239], s[92:93] op_sel_hi:[1,0]
	v_pk_mul_f32 v[248:249], v[240:241], s[92:93] op_sel_hi:[1,0]
	v_pk_mul_f32 v[250:251], v[242:243], s[92:93] op_sel_hi:[1,0]
	v_exp_f32_e32 v244, v244
	v_exp_f32_e32 v245, v245
	v_exp_f32_e32 v246, v246
	v_exp_f32_e32 v247, v247
	v_exp_f32_e32 v248, v248
	v_exp_f32_e32 v249, v249
	v_exp_f32_e32 v250, v250
	v_exp_f32_e32 v251, v251
	v_pk_mul_f32 v[236:237], v[236:237], v[70:71]
	v_pk_mul_f32 v[238:239], v[238:239], v[72:73]
	v_pk_mul_f32 v[240:241], v[240:241], v[66:67]
	v_pk_mul_f32 v[242:243], v[242:243], v[68:69]
	v_pk_add_f32 v[244:245], v[244:245], 1.0 op_sel_hi:[1,0]
	v_pk_add_f32 v[246:247], v[246:247], 1.0 op_sel_hi:[1,0]
	v_pk_add_f32 v[248:249], v[248:249], 1.0 op_sel_hi:[1,0]
	v_pk_add_f32 v[250:251], v[250:251], 1.0 op_sel_hi:[1,0]
	v_rcp_f32_e32 v244, v244
	v_rcp_f32_e32 v245, v245
	v_rcp_f32_e32 v246, v246
	v_rcp_f32_e32 v247, v247
	v_rcp_f32_e32 v248, v248
	v_rcp_f32_e32 v249, v249
	v_rcp_f32_e32 v250, v250
	v_rcp_f32_e32 v251, v251
	s_nop 0
	v_pk_mul_f32 v[236:237], v[236:237], v[244:245]
	v_pk_mul_f32 v[238:239], v[238:239], v[246:247]
	v_pk_mul_f32 v[240:241], v[240:241], v[248:249]
	v_pk_mul_f32 v[242:243], v[242:243], v[250:251]
	v_cvt_pk_bf16_f32 v216, v236, v237
	v_cvt_pk_bf16_f32 v217, v238, v239
	v_cvt_pk_bf16_f32 v218, v240, v241
	v_cvt_pk_bf16_f32 v219, v242, v243
	global_store_dwordx4 v[220:221], v[216:219], off sc1
	v_lshl_add_u64 v[220:221], v[220:221], 0, s[98:99]
	v_pk_mul_f32 v[62:63], v[62:63], v[170:171] op_sel_hi:[1,0]
	v_pk_mul_f32 v[64:65], v[64:65], v[170:171] op_sel_hi:[1,0]
	v_pk_mul_f32 v[58:59], v[58:59], v[170:171] op_sel_hi:[1,0]
	v_pk_mul_f32 v[60:61], v[60:61], v[170:171] op_sel_hi:[1,0]
	v_lshl_add_u32 v167, v163, 2, s64
	ds_read_b128 v[192:195], v167
	ds_read_b128 v[196:199], v167 offset:16
	ds_read_b128 v[200:203], v167 offset:128
	ds_read_b128 v[204:207], v167 offset:144
	v_pk_fma_f32 v[236:237], v[122:123], v[62:63], v[130:131]
	v_pk_fma_f32 v[238:239], v[124:125], v[64:65], v[132:133]
	v_pk_fma_f32 v[240:241], v[126:127], v[58:59], v[134:135]
	v_pk_fma_f32 v[242:243], v[128:129], v[60:61], v[136:137]
	v_pk_mul_f32 v[54:55], v[54:55], v[170:171] op_sel_hi:[1,0]
; #define PG8_LAS __attribute__((address_space(3)))
; __device__ __forceinline__ unsigned cvt_pk_bf16(float lo, float hi) { unsigned r; asm volatile("v_cvt_pk_bf16_f32 %0, %1, %2" : "=v"(r) : "v"(lo), "v"(hi)); return r; }
; __device__ __forceinline__ float dpp_shl15(float v) { return __builtin_bit_cast(float, __builtin_amdgcn_update_dpp(0, __builtin_bit_cast(int, v), 0x10F, 0xf, 0xf, true)); }
; __device__ __forceinline__ float dpp_shl14(float v) { return __builtin_bit_cast(float, __builtin_amdgcn_update_dpp(0, __builtin_bit_cast(int, v), 0x10E, 0xf, 0xf, true)); }
;     __device__ __forceinline__ void operator()(const f32x4 (&acc)[2][2][4][2], const Unit& u, int wr, int wc, int fr, int fq) const {
;     ...
;                 if (m == 0) {
;                     if (ai == 1 || wr == 1) { const int sw = ((ai == 1 && wr == 0) ? 4 : 0) + wc, sai = (ai == 1 && wr == 1) ? 1 : 0;
;                         const PG8_LAS f32x4* xp = (const PG8_LAS f32x4*)(X + ((sw * 2 + sai) * 2) * 32 + fq * 8); const f32x4 h0a = xp[0], h0b = xp[1], h1a = xp[8], h1b = xp[9];
;                         aa += w1a * (h1a * m0) + w0a * (h0a * m0 + h1a * m1); ab += w1b * (h1b * m0) + w0b * (h0b * m0 + h1b * m1); }
;                 } else {
; #pragma unroll
;                     for (int c = 0; c < 4; ++c) { aa[c] = __builtin_fmaf(w1a[c], dpp_shl15(pa[c]), aa[c]); ab[c] = __builtin_fmaf(w1b[c], dpp_shl15(pb[c]), ab[c]);
;                         aa[c] = __builtin_fmaf(w0a[c], dpp_shl14(pa[c]), aa[c]); ab[c] = __builtin_fmaf(w0b[c], dpp_shl14(pb[c]), ab[c]); }
;                 }
;                 const f32x4 ga = acc[ai][1][m][0] * rs, gb = acc[ai][1][m][1] * rs;
;                 f32x4 ea = aa * -1.4426950408889634f, eb = ab * -1.4426950408889634f;
; #pragma unroll
;                 for (int c = 0; c < 4; ++c) { ea[c] = __builtin_amdgcn_exp2f(ea[c]); eb[c] = __builtin_amdgcn_exp2f(eb[c]); }
;                 ea = ea + 1.0f; eb = eb + 1.0f;
; #pragma unroll
;                 for (int c = 0; c < 4; ++c) { ea[c] = __builtin_amdgcn_rcpf(ea[c]); eb[c] = __builtin_amdgcn_rcpf(eb[c]); }
;                 const f32x4 oa = (aa * ga) * ea, ob = (ab * gb) * eb;
;                 u32x4 w; w.x = cvt_pk_bf16(oa[0], oa[1]); w.y = cvt_pk_bf16(oa[2], oa[3]); w.z = cvt_pk_bf16(ob[0], ob[1]); w.w = cvt_pk_bf16(ob[2], ob[3]);
;                 *(u32x4*)(act + (size_t)row * FF + col) = w;
	v_pk_mul_f32 v[56:57], v[56:57], v[170:171] op_sel_hi:[1,0]
	v_pk_mul_f32 v[50:51], v[50:51], v[170:171] op_sel_hi:[1,0]
	v_pk_mul_f32 v[52:53], v[52:53], v[170:171] op_sel_hi:[1,0]
	v_fmac_f32_dpp v236, v62, v114 row_shr:1 row_mask:0xf bank_mask:0xf bound_ctrl:1
	v_fmac_f32_dpp v237, v63, v115 row_shr:1 row_mask:0xf bank_mask:0xf bound_ctrl:1
	v_fmac_f32_dpp v238, v64, v116 row_shr:1 row_mask:0xf bank_mask:0xf bound_ctrl:1
	v_fmac_f32_dpp v239, v65, v117 row_shr:1 row_mask:0xf bank_mask:0xf bound_ctrl:1
	v_fmac_f32_dpp v240, v58, v118 row_shr:1 row_mask:0xf bank_mask:0xf bound_ctrl:1
	v_fmac_f32_dpp v241, v59, v119 row_shr:1 row_mask:0xf bank_mask:0xf bound_ctrl:1
	v_fmac_f32_dpp v242, v60, v120 row_shr:1 row_mask:0xf bank_mask:0xf bound_ctrl:1
	v_fmac_f32_dpp v243, v61, v121 row_shr:1 row_mask:0xf bank_mask:0xf bound_ctrl:1
	v_fmac_f32_dpp v236, v62, v106 row_shr:2 row_mask:0xf bank_mask:0xf bound_ctrl:1
	v_fmac_f32_dpp v237, v63, v107 row_shr:2 row_mask:0xf bank_mask:0xf bound_ctrl:1
	v_fmac_f32_dpp v238, v64, v108 row_shr:2 row_mask:0xf bank_mask:0xf bound_ctrl:1
	v_fmac_f32_dpp v239, v65, v109 row_shr:2 row_mask:0xf bank_mask:0xf bound_ctrl:1
	v_fmac_f32_dpp v240, v58, v110 row_shr:2 row_mask:0xf bank_mask:0xf bound_ctrl:1
	v_fmac_f32_dpp v241, v59, v111 row_shr:2 row_mask:0xf bank_mask:0xf bound_ctrl:1
	v_fmac_f32_dpp v242, v60, v112 row_shr:2 row_mask:0xf bank_mask:0xf bound_ctrl:1
	v_fmac_f32_dpp v243, v61, v113 row_shr:2 row_mask:0xf bank_mask:0xf bound_ctrl:1
	v_cmp_eq_u32_e64 s[44:45], 0, v1
	v_cmp_eq_u32_e64 s[46:47], 1, v1
	s_waitcnt lgkmcnt(0)
	s_mov_b64 exec, s[44:45]
	v_pk_fma_f32 v[236:237], v[114:115], v[200:201], v[236:237]
	v_pk_fma_f32 v[238:239], v[116:117], v[202:203], v[238:239]
	v_pk_fma_f32 v[240:241], v[118:119], v[204:205], v[240:241]
	v_pk_fma_f32 v[242:243], v[120:121], v[206:207], v[242:243]
	v_pk_fma_f32 v[236:237], v[106:107], v[192:193], v[236:237]
	v_pk_fma_f32 v[238:239], v[108:109], v[194:195], v[238:239]
	v_pk_fma_f32 v[240:241], v[110:111], v[196:197], v[240:241]
	v_pk_fma_f32 v[242:243], v[112:113], v[198:199], v[242:243]
	s_mov_b64 exec, s[46:47]
	v_pk_fma_f32 v[236:237], v[106:107], v[200:201], v[236:237]
	v_pk_fma_f32 v[238:239], v[108:109], v[202:203], v[238:239]
	v_pk_fma_f32 v[240:241], v[110:111], v[204:205], v[240:241]
	v_pk_fma_f32 v[242:243], v[112:113], v[206:207], v[242:243]
	s_mov_b64 exec, -1
	v_pk_mul_f32 v[244:245], v[236:237], s[92:93] op_sel_hi:[1,0]
	v_pk_mul_f32 v[246:247], v[238:239], s[92:93] op_sel_hi:[1,0]
	v_pk_mul_f32 v[248:249], v[240:241], s[92:93] op_sel_hi:[1,0]
	v_pk_mul_f32 v[250:251], v[242:243], s[92:93] op_sel_hi:[1,0]
	v_exp_f32_e32 v244, v244
	v_exp_f32_e32 v245, v245
	v_exp_f32_e32 v246, v246
	v_exp_f32_e32 v247, v247
	v_exp_f32_e32 v248, v248
	v_exp_f32_e32 v249, v249
	v_exp_f32_e32 v250, v250
	v_exp_f32_e32 v251, v251
	v_pk_mul_f32 v[236:237], v[236:237], v[54:55]
	v_pk_mul_f32 v[238:239], v[238:239], v[56:57]
	v_pk_mul_f32 v[240:241], v[240:241], v[50:51]
	v_pk_mul_f32 v[242:243], v[242:243], v[52:53]
	v_pk_add_f32 v[244:245], v[244:245], 1.0 op_sel_hi:[1,0]
	v_pk_add_f32 v[246:247], v[246:247], 1.0 op_sel_hi:[1,0]
	v_pk_add_f32 v[248:249], v[248:249], 1.0 op_sel_hi:[1,0]
	v_pk_add_f32 v[250:251], v[250:251], 1.0 op_sel_hi:[1,0]
	v_rcp_f32_e32 v244, v244
	v_rcp_f32_e32 v245, v245
	v_rcp_f32_e32 v246, v246
	v_rcp_f32_e32 v247, v247
	v_rcp_f32_e32 v248, v248
	v_rcp_f32_e32 v249, v249
	v_rcp_f32_e32 v250, v250
	v_rcp_f32_e32 v251, v251
	s_nop 0
	v_pk_mul_f32 v[236:237], v[236:237], v[244:245]
	v_pk_mul_f32 v[238:239], v[238:239], v[246:247]
	v_pk_mul_f32 v[240:241], v[240:241], v[248:249]
	v_pk_mul_f32 v[242:243], v[242:243], v[250:251]
	v_cvt_pk_bf16_f32 v216, v236, v237
	v_cvt_pk_bf16_f32 v217, v238, v239
	v_cvt_pk_bf16_f32 v218, v240, v241
	v_cvt_pk_bf16_f32 v219, v242, v243
	global_store_dwordx4 v[220:221], v[216:219], off sc1
	v_lshl_add_u64 v[220:221], v[220:221], 0, s[100:101]
	v_pk_mul_f32 v[46:47], v[46:47], v[172:173] op_sel_hi:[1,0]
	v_pk_mul_f32 v[48:49], v[48:49], v[172:173] op_sel_hi:[1,0]
	v_pk_mul_f32 v[42:43], v[42:43], v[172:173] op_sel_hi:[1,0]
	v_pk_mul_f32 v[44:45], v[44:45], v[172:173] op_sel_hi:[1,0]
	v_pk_fma_f32 v[236:237], v[122:123], v[46:47], v[130:131]
	v_pk_fma_f32 v[238:239], v[124:125], v[48:49], v[132:133]
	v_pk_fma_f32 v[240:241], v[126:127], v[42:43], v[134:135]
	v_pk_fma_f32 v[242:243], v[128:129], v[44:45], v[136:137]
	v_pk_mul_f32 v[38:39], v[38:39], v[172:173] op_sel_hi:[1,0]
	v_pk_mul_f32 v[40:41], v[40:41], v[172:173] op_sel_hi:[1,0]
	v_pk_mul_f32 v[34:35], v[34:35], v[172:173] op_sel_hi:[1,0]
	v_pk_mul_f32 v[36:37], v[36:37], v[172:173] op_sel_hi:[1,0]
	v_fmac_f32_dpp v236, v46, v114 row_shr:1 row_mask:0xf bank_mask:0xf bound_ctrl:1
	v_fmac_f32_dpp v237, v47, v115 row_shr:1 row_mask:0xf bank_mask:0xf bound_ctrl:1
	v_fmac_f32_dpp v238, v48, v116 row_shr:1 row_mask:0xf bank_mask:0xf bound_ctrl:1
	v_fmac_f32_dpp v239, v49, v117 row_shr:1 row_mask:0xf bank_mask:0xf bound_ctrl:1
	v_fmac_f32_dpp v240, v42, v118 row_shr:1 row_mask:0xf bank_mask:0xf bound_ctrl:1
	v_fmac_f32_dpp v241, v43, v119 row_shr:1 row_mask:0xf bank_mask:0xf bound_ctrl:1
	v_fmac_f32_dpp v242, v44, v120 row_shr:1 row_mask:0xf bank_mask:0xf bound_ctrl:1
	v_fmac_f32_dpp v243, v45, v121 row_shr:1 row_mask:0xf bank_mask:0xf bound_ctrl:1
	v_fmac_f32_dpp v236, v46, v106 row_shr:2 row_mask:0xf bank_mask:0xf bound_ctrl:1
	v_fmac_f32_dpp v237, v47, v107 row_shr:2 row_mask:0xf bank_mask:0xf bound_ctrl:1
	v_fmac_f32_dpp v238, v48, v108 row_shr:2 row_mask:0xf bank_mask:0xf bound_ctrl:1
	v_fmac_f32_dpp v239, v49, v109 row_shr:2 row_mask:0xf bank_mask:0xf bound_ctrl:1
;     __device__ __forceinline__ void operator()(const f32x4 (&acc)[2][2][4][2], const Unit& u, int wr, int wc, int fr, int fq) const {
;     ...
;             for (int m = 0; m < 4; ++m) {
;                 const int row = row0 + ai * HALF + m * 16; const float rs = rsv[m];
;                 const f32x4 ca = acc[ai][0][m][0] * rs, cb_ = acc[ai][0][m][1] * rs;
;                 f32x4 aa = w2a * ca + ba, ab = w2b * cb_ + bb;
; #pragma unroll
;                 for (int c = 0; c < 4; ++c) { aa[c] = __builtin_fmaf(w1a[c], dpp_shr1(ca[c]), aa[c]); ab[c] = __builtin_fmaf(w1b[c], dpp_shr1(cb_[c]), ab[c]);
;                     aa[c] = __builtin_fmaf(w0a[c], dpp_shr2(ca[c]), aa[c]); ab[c] = __builtin_fmaf(w0b[c], dpp_shr2(cb_[c]), ab[c]); }
;                 if (m == 0) {
;                     if (ai == 1 || wr == 1) { const int sw = ((ai == 1 && wr == 0) ? 4 : 0) + wc, sai = (ai == 1 && wr == 1) ? 1 : 0;
;                         const PG8_LAS f32x4* xp = (const PG8_LAS f32x4*)(X + ((sw * 2 + sai) * 2) * 32 + fq * 8); const f32x4 h0a = xp[0], h0b = xp[1], h1a = xp[8], h1b = xp[9];
;                         aa += w1a * (h1a * m0) + w0a * (h0a * m0 + h1a * m1); ab += w1b * (h1b * m0) + w0b * (h0b * m0 + h1b * m1); }
;                 } else {
; #pragma unroll
;                     for (int c = 0; c < 4; ++c) { aa[c] = __builtin_fmaf(w1a[c], dpp_shl15(pa[c]), aa[c]); ab[c] = __builtin_fmaf(w1b[c], dpp_shl15(pb[c]), ab[c]);
;                         aa[c] = __builtin_fmaf(w0a[c], dpp_shl14(pa[c]), aa[c]); ab[c] = __builtin_fmaf(w0b[c], dpp_shl14(pb[c]), ab[c]); }
;                 }
;                 const f32x4 ga = acc[ai][1][m][0] * rs, gb = acc[ai][1][m][1] * rs;
;                 f32x4 ea = aa * -1.4426950408889634f, eb = ab * -1.4426950408889634f;
; #pragma unroll
;                 for (int c = 0; c < 4; ++c) { ea[c] = __builtin_amdgcn_exp2f(ea[c]); eb[c] = __builtin_amdgcn_exp2f(eb[c]); }
;                 ea = ea + 1.0f; eb = eb + 1.0f;
; #pragma unroll
;                 for (int c = 0; c < 4; ++c) { ea[c] = __builtin_amdgcn_rcpf(ea[c]); eb[c] = __builtin_amdgcn_rcpf(eb[c]); }
;                 const f32x4 oa = (aa * ga) * ea, ob = (ab * gb) * eb;
;                 u32x4 w; w.x = cvt_pk_bf16(oa[0], oa[1]); w.y = cvt_pk_bf16(oa[2], oa[3]); w.z = cvt_pk_bf16(ob[0], ob[1]); w.w = cvt_pk_bf16(ob[2], ob[3]);
;                 *(u32x4*)(act + (size_t)row * FF + col) = w;
	v_fmac_f32_dpp v240, v42, v110 row_shr:2 row_mask:0xf bank_mask:0xf bound_ctrl:1
	v_fmac_f32_dpp v241, v43, v111 row_shr:2 row_mask:0xf bank_mask:0xf bound_ctrl:1
	v_fmac_f32_dpp v242, v44, v112 row_shr:2 row_mask:0xf bank_mask:0xf bound_ctrl:1
	v_fmac_f32_dpp v243, v45, v113 row_shr:2 row_mask:0xf bank_mask:0xf bound_ctrl:1
	v_fmac_f32_dpp v236, v62, v114 row_shl:15 row_mask:0xf bank_mask:0xf bound_ctrl:1
	v_fmac_f32_dpp v237, v63, v115 row_shl:15 row_mask:0xf bank_mask:0xf bound_ctrl:1
	v_fmac_f32_dpp v238, v64, v116 row_shl:15 row_mask:0xf bank_mask:0xf bound_ctrl:1
	v_fmac_f32_dpp v239, v65, v117 row_shl:15 row_mask:0xf bank_mask:0xf bound_ctrl:1
	v_fmac_f32_dpp v240, v58, v118 row_shl:15 row_mask:0xf bank_mask:0xf bound_ctrl:1
	v_fmac_f32_dpp v241, v59, v119 row_shl:15 row_mask:0xf bank_mask:0xf bound_ctrl:1
	v_fmac_f32_dpp v242, v60, v120 row_shl:15 row_mask:0xf bank_mask:0xf bound_ctrl:1
	v_fmac_f32_dpp v243, v61, v121 row_shl:15 row_mask:0xf bank_mask:0xf bound_ctrl:1
	v_fmac_f32_dpp v236, v62, v106 row_shl:14 row_mask:0xf bank_mask:0xf bound_ctrl:1
	v_fmac_f32_dpp v237, v63, v107 row_shl:14 row_mask:0xf bank_mask:0xf bound_ctrl:1
	v_fmac_f32_dpp v238, v64, v108 row_shl:14 row_mask:0xf bank_mask:0xf bound_ctrl:1
	v_fmac_f32_dpp v239, v65, v109 row_shl:14 row_mask:0xf bank_mask:0xf bound_ctrl:1
	v_fmac_f32_dpp v240, v58, v110 row_shl:14 row_mask:0xf bank_mask:0xf bound_ctrl:1
	v_fmac_f32_dpp v241, v59, v111 row_shl:14 row_mask:0xf bank_mask:0xf bound_ctrl:1
	v_fmac_f32_dpp v242, v60, v112 row_shl:14 row_mask:0xf bank_mask:0xf bound_ctrl:1
	v_fmac_f32_dpp v243, v61, v113 row_shl:14 row_mask:0xf bank_mask:0xf bound_ctrl:1
	v_pk_mul_f32 v[244:245], v[236:237], s[92:93] op_sel_hi:[1,0]
	v_pk_mul_f32 v[246:247], v[238:239], s[92:93] op_sel_hi:[1,0]
	v_pk_mul_f32 v[248:249], v[240:241], s[92:93] op_sel_hi:[1,0]
	v_pk_mul_f32 v[250:251], v[242:243], s[92:93] op_sel_hi:[1,0]
	v_exp_f32_e32 v244, v244
	v_exp_f32_e32 v245, v245
	v_exp_f32_e32 v246, v246
	v_exp_f32_e32 v247, v247
	v_exp_f32_e32 v248, v248
	v_exp_f32_e32 v249, v249
	v_exp_f32_e32 v250, v250
	v_exp_f32_e32 v251, v251
	v_pk_mul_f32 v[236:237], v[236:237], v[38:39]
	v_pk_mul_f32 v[238:239], v[238:239], v[40:41]
	v_pk_mul_f32 v[240:241], v[240:241], v[34:35]
	v_pk_mul_f32 v[242:243], v[242:243], v[36:37]
	v_pk_add_f32 v[244:245], v[244:245], 1.0 op_sel_hi:[1,0]
	v_pk_add_f32 v[246:247], v[246:247], 1.0 op_sel_hi:[1,0]
	v_pk_add_f32 v[248:249], v[248:249], 1.0 op_sel_hi:[1,0]
	v_pk_add_f32 v[250:251], v[250:251], 1.0 op_sel_hi:[1,0]
	v_rcp_f32_e32 v244, v244
	v_rcp_f32_e32 v245, v245
	v_rcp_f32_e32 v246, v246
	v_rcp_f32_e32 v247, v247
	v_rcp_f32_e32 v248, v248
	v_rcp_f32_e32 v249, v249
	v_rcp_f32_e32 v250, v250
	v_rcp_f32_e32 v251, v251
	s_nop 0
	v_pk_mul_f32 v[236:237], v[236:237], v[244:245]
	v_pk_mul_f32 v[238:239], v[238:239], v[246:247]
	v_pk_mul_f32 v[240:241], v[240:241], v[248:249]
	v_pk_mul_f32 v[242:243], v[242:243], v[250:251]
	v_cvt_pk_bf16_f32 v216, v236, v237
	v_cvt_pk_bf16_f32 v217, v238, v239
	v_cvt_pk_bf16_f32 v218, v240, v241
	v_cvt_pk_bf16_f32 v219, v242, v243
	global_store_dwordx4 v[220:221], v[216:219], off sc1
	v_lshl_add_u64 v[220:221], v[220:221], 0, s[100:101]
	v_pk_mul_f32 v[30:31], v[30:31], v[232:233] op_sel_hi:[1,0]
	v_pk_mul_f32 v[32:33], v[32:33], v[232:233] op_sel_hi:[1,0]
	v_pk_mul_f32 v[26:27], v[26:27], v[232:233] op_sel_hi:[1,0]
	v_pk_mul_f32 v[28:29], v[28:29], v[232:233] op_sel_hi:[1,0]
	v_pk_fma_f32 v[236:237], v[122:123], v[30:31], v[130:131]
	v_pk_fma_f32 v[238:239], v[124:125], v[32:33], v[132:133]
	v_pk_fma_f32 v[240:241], v[126:127], v[26:27], v[134:135]
	v_pk_fma_f32 v[242:243], v[128:129], v[28:29], v[136:137]
	v_pk_mul_f32 v[22:23], v[22:23], v[232:233] op_sel_hi:[1,0]
	v_pk_mul_f32 v[24:25], v[24:25], v[232:233] op_sel_hi:[1,0]
	v_pk_mul_f32 v[18:19], v[18:19], v[232:233] op_sel_hi:[1,0]
	v_pk_mul_f32 v[20:21], v[20:21], v[232:233] op_sel_hi:[1,0]
	v_fmac_f32_dpp v236, v30, v114 row_shr:1 row_mask:0xf bank_mask:0xf bound_ctrl:1
	v_fmac_f32_dpp v237, v31, v115 row_shr:1 row_mask:0xf bank_mask:0xf bound_ctrl:1
	v_fmac_f32_dpp v238, v32, v116 row_shr:1 row_mask:0xf bank_mask:0xf bound_ctrl:1
	v_fmac_f32_dpp v239, v33, v117 row_shr:1 row_mask:0xf bank_mask:0xf bound_ctrl:1
	v_fmac_f32_dpp v240, v26, v118 row_shr:1 row_mask:0xf bank_mask:0xf bound_ctrl:1
	v_fmac_f32_dpp v241, v27, v119 row_shr:1 row_mask:0xf bank_mask:0xf bound_ctrl:1
	v_fmac_f32_dpp v242, v28, v120 row_shr:1 row_mask:0xf bank_mask:0xf bound_ctrl:1
	v_fmac_f32_dpp v243, v29, v121 row_shr:1 row_mask:0xf bank_mask:0xf bound_ctrl:1
	v_fmac_f32_dpp v236, v30, v106 row_shr:2 row_mask:0xf bank_mask:0xf bound_ctrl:1
	v_fmac_f32_dpp v237, v31, v107 row_shr:2 row_mask:0xf bank_mask:0xf bound_ctrl:1
	v_fmac_f32_dpp v238, v32, v108 row_shr:2 row_mask:0xf bank_mask:0xf bound_ctrl:1
	v_fmac_f32_dpp v239, v33, v109 row_shr:2 row_mask:0xf bank_mask:0xf bound_ctrl:1
	v_fmac_f32_dpp v240, v26, v110 row_shr:2 row_mask:0xf bank_mask:0xf bound_ctrl:1
	v_fmac_f32_dpp v241, v27, v111 row_shr:2 row_mask:0xf bank_mask:0xf bound_ctrl:1
	v_fmac_f32_dpp v242, v28, v112 row_shr:2 row_mask:0xf bank_mask:0xf bound_ctrl:1
	v_fmac_f32_dpp v243, v29, v113 row_shr:2 row_mask:0xf bank_mask:0xf bound_ctrl:1
	v_fmac_f32_dpp v236, v46, v114 row_shl:15 row_mask:0xf bank_mask:0xf bound_ctrl:1
	v_fmac_f32_dpp v237, v47, v115 row_shl:15 row_mask:0xf bank_mask:0xf bound_ctrl:1
	v_fmac_f32_dpp v238, v48, v116 row_shl:15 row_mask:0xf bank_mask:0xf bound_ctrl:1
	v_fmac_f32_dpp v239, v49, v117 row_shl:15 row_mask:0xf bank_mask:0xf bound_ctrl:1
	v_fmac_f32_dpp v240, v42, v118 row_shl:15 row_mask:0xf bank_mask:0xf bound_ctrl:1
;     __device__ __forceinline__ void operator()(const f32x4 (&acc)[2][2][4][2], const Unit& u, int wr, int wc, int fr, int fq) const {
;     ...
;             for (int m = 0; m < 4; ++m) {
;                 const int row = row0 + ai * HALF + m * 16; const float rs = rsv[m];
;                 const f32x4 ca = acc[ai][0][m][0] * rs, cb_ = acc[ai][0][m][1] * rs;
;                 f32x4 aa = w2a * ca + ba, ab = w2b * cb_ + bb;
; #pragma unroll
;                 for (int c = 0; c < 4; ++c) { aa[c] = __builtin_fmaf(w1a[c], dpp_shr1(ca[c]), aa[c]); ab[c] = __builtin_fmaf(w1b[c], dpp_shr1(cb_[c]), ab[c]);
;                     aa[c] = __builtin_fmaf(w0a[c], dpp_shr2(ca[c]), aa[c]); ab[c] = __builtin_fmaf(w0b[c], dpp_shr2(cb_[c]), ab[c]); }
;                 if (m == 0) {
;                     if (ai == 1 || wr == 1) { const int sw = ((ai == 1 && wr == 0) ? 4 : 0) + wc, sai = (ai == 1 && wr == 1) ? 1 : 0;
;                         const PG8_LAS f32x4* xp = (const PG8_LAS f32x4*)(X + ((sw * 2 + sai) * 2) * 32 + fq * 8); const f32x4 h0a = xp[0], h0b = xp[1], h1a = xp[8], h1b = xp[9];
;                         aa += w1a * (h1a * m0) + w0a * (h0a * m0 + h1a * m1); ab += w1b * (h1b * m0) + w0b * (h0b * m0 + h1b * m1); }
;                 } else {
; #pragma unroll
;                     for (int c = 0; c < 4; ++c) { aa[c] = __builtin_fmaf(w1a[c], dpp_shl15(pa[c]), aa[c]); ab[c] = __builtin_fmaf(w1b[c], dpp_shl15(pb[c]), ab[c]);
;                         aa[c] = __builtin_fmaf(w0a[c], dpp_shl14(pa[c]), aa[c]); ab[c] = __builtin_fmaf(w0b[c], dpp_shl14(pb[c]), ab[c]); }
;                 }
;                 const f32x4 ga = acc[ai][1][m][0] * rs, gb = acc[ai][1][m][1] * rs;
;                 f32x4 ea = aa * -1.4426950408889634f, eb = ab * -1.4426950408889634f;
; #pragma unroll
;                 for (int c = 0; c < 4; ++c) { ea[c] = __builtin_amdgcn_exp2f(ea[c]); eb[c] = __builtin_amdgcn_exp2f(eb[c]); }
;                 ea = ea + 1.0f; eb = eb + 1.0f;
; #pragma unroll
;                 for (int c = 0; c < 4; ++c) { ea[c] = __builtin_amdgcn_rcpf(ea[c]); eb[c] = __builtin_amdgcn_rcpf(eb[c]); }
;                 const f32x4 oa = (aa * ga) * ea, ob = (ab * gb) * eb;
;                 u32x4 w; w.x = cvt_pk_bf16(oa[0], oa[1]); w.y = cvt_pk_bf16(oa[2], oa[3]); w.z = cvt_pk_bf16(ob[0], ob[1]); w.w = cvt_pk_bf16(ob[2], ob[3]);
;                 *(u32x4*)(act + (size_t)row * FF + col) = w;
	v_fmac_f32_dpp v241, v43, v119 row_shl:15 row_mask:0xf bank_mask:0xf bound_ctrl:1
	v_fmac_f32_dpp v242, v44, v120 row_shl:15 row_mask:0xf bank_mask:0xf bound_ctrl:1
	v_fmac_f32_dpp v243, v45, v121 row_shl:15 row_mask:0xf bank_mask:0xf bound_ctrl:1
	v_fmac_f32_dpp v236, v46, v106 row_shl:14 row_mask:0xf bank_mask:0xf bound_ctrl:1
	v_fmac_f32_dpp v237, v47, v107 row_shl:14 row_mask:0xf bank_mask:0xf bound_ctrl:1
	v_fmac_f32_dpp v238, v48, v108 row_shl:14 row_mask:0xf bank_mask:0xf bound_ctrl:1
	v_fmac_f32_dpp v239, v49, v109 row_shl:14 row_mask:0xf bank_mask:0xf bound_ctrl:1
	v_fmac_f32_dpp v240, v42, v110 row_shl:14 row_mask:0xf bank_mask:0xf bound_ctrl:1
	v_fmac_f32_dpp v241, v43, v111 row_shl:14 row_mask:0xf bank_mask:0xf bound_ctrl:1
	v_fmac_f32_dpp v242, v44, v112 row_shl:14 row_mask:0xf bank_mask:0xf bound_ctrl:1
	v_fmac_f32_dpp v243, v45, v113 row_shl:14 row_mask:0xf bank_mask:0xf bound_ctrl:1
	v_pk_mul_f32 v[244:245], v[236:237], s[92:93] op_sel_hi:[1,0]
	v_pk_mul_f32 v[246:247], v[238:239], s[92:93] op_sel_hi:[1,0]
	v_pk_mul_f32 v[248:249], v[240:241], s[92:93] op_sel_hi:[1,0]
	v_pk_mul_f32 v[250:251], v[242:243], s[92:93] op_sel_hi:[1,0]
	v_exp_f32_e32 v244, v244
	v_exp_f32_e32 v245, v245
	v_exp_f32_e32 v246, v246
	v_exp_f32_e32 v247, v247
	v_exp_f32_e32 v248, v248
	v_exp_f32_e32 v249, v249
	v_exp_f32_e32 v250, v250
	v_exp_f32_e32 v251, v251
	v_pk_mul_f32 v[236:237], v[236:237], v[22:23]
	v_pk_mul_f32 v[238:239], v[238:239], v[24:25]
	v_pk_mul_f32 v[240:241], v[240:241], v[18:19]
	v_pk_mul_f32 v[242:243], v[242:243], v[20:21]
	v_pk_add_f32 v[244:245], v[244:245], 1.0 op_sel_hi:[1,0]
	v_pk_add_f32 v[246:247], v[246:247], 1.0 op_sel_hi:[1,0]
	v_pk_add_f32 v[248:249], v[248:249], 1.0 op_sel_hi:[1,0]
	v_pk_add_f32 v[250:251], v[250:251], 1.0 op_sel_hi:[1,0]
	v_rcp_f32_e32 v244, v244
	v_rcp_f32_e32 v245, v245
	v_rcp_f32_e32 v246, v246
	v_rcp_f32_e32 v247, v247
	v_rcp_f32_e32 v248, v248
	v_rcp_f32_e32 v249, v249
	v_rcp_f32_e32 v250, v250
	v_rcp_f32_e32 v251, v251
	s_nop 0
	v_pk_mul_f32 v[236:237], v[236:237], v[244:245]
	v_pk_mul_f32 v[238:239], v[238:239], v[246:247]
	v_pk_mul_f32 v[240:241], v[240:241], v[248:249]
	v_pk_mul_f32 v[242:243], v[242:243], v[250:251]
	v_cvt_pk_bf16_f32 v216, v236, v237
	v_cvt_pk_bf16_f32 v217, v238, v239
	v_cvt_pk_bf16_f32 v218, v240, v241
	v_cvt_pk_bf16_f32 v219, v242, v243
	global_store_dwordx4 v[220:221], v[216:219], off sc1
	v_lshl_add_u64 v[220:221], v[220:221], 0, s[100:101]
	v_pk_fma_f32 v[236:237], v[122:123], v[14:15], v[130:131]
	v_pk_fma_f32 v[238:239], v[124:125], v[16:17], v[132:133]
	v_pk_fma_f32 v[240:241], v[126:127], v[10:11], v[134:135]
	v_pk_fma_f32 v[242:243], v[128:129], v[12:13], v[136:137]
	v_pk_mul_f32 v[6:7], v[6:7], v[234:235] op_sel_hi:[1,0]
	v_pk_mul_f32 v[8:9], v[8:9], v[234:235] op_sel_hi:[1,0]
	v_pk_mul_f32 v[2:3], v[2:3], v[234:235] op_sel_hi:[1,0]
	v_pk_mul_f32 v[4:5], v[4:5], v[234:235] op_sel_hi:[1,0]
	v_fmac_f32_dpp v236, v14, v114 row_shr:1 row_mask:0xf bank_mask:0xf bound_ctrl:1
	v_fmac_f32_dpp v237, v15, v115 row_shr:1 row_mask:0xf bank_mask:0xf bound_ctrl:1
	v_fmac_f32_dpp v238, v16, v116 row_shr:1 row_mask:0xf bank_mask:0xf bound_ctrl:1
	v_fmac_f32_dpp v239, v17, v117 row_shr:1 row_mask:0xf bank_mask:0xf bound_ctrl:1
	v_fmac_f32_dpp v240, v10, v118 row_shr:1 row_mask:0xf bank_mask:0xf bound_ctrl:1
	v_fmac_f32_dpp v241, v11, v119 row_shr:1 row_mask:0xf bank_mask:0xf bound_ctrl:1
	v_fmac_f32_dpp v242, v12, v120 row_shr:1 row_mask:0xf bank_mask:0xf bound_ctrl:1
	v_fmac_f32_dpp v243, v13, v121 row_shr:1 row_mask:0xf bank_mask:0xf bound_ctrl:1
	v_fmac_f32_dpp v236, v14, v106 row_shr:2 row_mask:0xf bank_mask:0xf bound_ctrl:1
; __device__ __forceinline__ unsigned cvt_pk_bf16(float lo, float hi) { unsigned r; asm volatile("v_cvt_pk_bf16_f32 %0, %1, %2" : "=v"(r) : "v"(lo), "v"(hi)); return r; }
; #define PG8_BAR __builtin_amdgcn_s_barrier()
;     __device__ __forceinline__ void operator()(const f32x4 (&acc)[2][2][4][2], const Unit& u, int wr, int wc, int fr, int fq) const {
;     ...
;                 const f32x4 ga = acc[ai][1][m][0] * rs, gb = acc[ai][1][m][1] * rs;
;                 f32x4 ea = aa * -1.4426950408889634f, eb = ab * -1.4426950408889634f;
; #pragma unroll
;                 for (int c = 0; c < 4; ++c) { ea[c] = __builtin_amdgcn_exp2f(ea[c]); eb[c] = __builtin_amdgcn_exp2f(eb[c]); }
;                 ea = ea + 1.0f; eb = eb + 1.0f;
; #pragma unroll
;                 for (int c = 0; c < 4; ++c) { ea[c] = __builtin_amdgcn_rcpf(ea[c]); eb[c] = __builtin_amdgcn_rcpf(eb[c]); }
;                 const f32x4 oa = (aa * ga) * ea, ob = (ab * gb) * eb;
;                 u32x4 w; w.x = cvt_pk_bf16(oa[0], oa[1]); w.y = cvt_pk_bf16(oa[2], oa[3]); w.z = cvt_pk_bf16(ob[0], ob[1]); w.w = cvt_pk_bf16(ob[2], ob[3]);
;                 *(u32x4*)(act + (size_t)row * FF + col) = w;
; template <class Epi, class Sched, bool ALIGN_EPI = false, bool SP2 = false>
; __device__ __forceinline__ void gemm_phase(PG8_LAS unsigned char* lds, const Gemm g, const Sched& S, const Epi& E) {
;     ...
;         if (!has_next) break;
; #pragma unroll
;         for (int a = 0; a < 2; ++a)
; #pragma unroll
;             for (int b = 0; b < 2; ++b)
; #pragma unroll
;                 for (int m = 0; m < 4; ++m)
; #pragma unroll
;                     for (int n = 0; n < 2; ++n) acc[a][b][m][n] = (f32x4){0.f, 0.f, 0.f, 0.f};
;         cur = nxt; cA = nA; cB = nB; ++ui;
;         if constexpr (ALIGN_EPI) { if (wr == 1) PG8_BAR; }
	v_fmac_f32_dpp v237, v15, v107 row_shr:2 row_mask:0xf bank_mask:0xf bound_ctrl:1
	v_fmac_f32_dpp v238, v16, v108 row_shr:2 row_mask:0xf bank_mask:0xf bound_ctrl:1
	v_fmac_f32_dpp v239, v17, v109 row_shr:2 row_mask:0xf bank_mask:0xf bound_ctrl:1
	v_fmac_f32_dpp v240, v10, v110 row_shr:2 row_mask:0xf bank_mask:0xf bound_ctrl:1
	v_fmac_f32_dpp v241, v11, v111 row_shr:2 row_mask:0xf bank_mask:0xf bound_ctrl:1
	v_fmac_f32_dpp v242, v12, v112 row_shr:2 row_mask:0xf bank_mask:0xf bound_ctrl:1
	v_fmac_f32_dpp v243, v13, v113 row_shr:2 row_mask:0xf bank_mask:0xf bound_ctrl:1
	v_fmac_f32_dpp v236, v30, v114 row_shl:15 row_mask:0xf bank_mask:0xf bound_ctrl:1
	v_fmac_f32_dpp v237, v31, v115 row_shl:15 row_mask:0xf bank_mask:0xf bound_ctrl:1
	v_fmac_f32_dpp v238, v32, v116 row_shl:15 row_mask:0xf bank_mask:0xf bound_ctrl:1
	v_fmac_f32_dpp v239, v33, v117 row_shl:15 row_mask:0xf bank_mask:0xf bound_ctrl:1
	v_fmac_f32_dpp v240, v26, v118 row_shl:15 row_mask:0xf bank_mask:0xf bound_ctrl:1
	v_fmac_f32_dpp v241, v27, v119 row_shl:15 row_mask:0xf bank_mask:0xf bound_ctrl:1
	v_fmac_f32_dpp v242, v28, v120 row_shl:15 row_mask:0xf bank_mask:0xf bound_ctrl:1
	v_fmac_f32_dpp v243, v29, v121 row_shl:15 row_mask:0xf bank_mask:0xf bound_ctrl:1
	v_fmac_f32_dpp v236, v30, v106 row_shl:14 row_mask:0xf bank_mask:0xf bound_ctrl:1
	v_fmac_f32_dpp v237, v31, v107 row_shl:14 row_mask:0xf bank_mask:0xf bound_ctrl:1
	v_fmac_f32_dpp v238, v32, v108 row_shl:14 row_mask:0xf bank_mask:0xf bound_ctrl:1
	v_fmac_f32_dpp v239, v33, v109 row_shl:14 row_mask:0xf bank_mask:0xf bound_ctrl:1
	v_fmac_f32_dpp v240, v26, v110 row_shl:14 row_mask:0xf bank_mask:0xf bound_ctrl:1
	v_fmac_f32_dpp v241, v27, v111 row_shl:14 row_mask:0xf bank_mask:0xf bound_ctrl:1
	v_fmac_f32_dpp v242, v28, v112 row_shl:14 row_mask:0xf bank_mask:0xf bound_ctrl:1
	v_fmac_f32_dpp v243, v29, v113 row_shl:14 row_mask:0xf bank_mask:0xf bound_ctrl:1
	v_pk_mul_f32 v[244:245], v[236:237], s[92:93] op_sel_hi:[1,0]
	v_pk_mul_f32 v[246:247], v[238:239], s[92:93] op_sel_hi:[1,0]
	v_pk_mul_f32 v[248:249], v[240:241], s[92:93] op_sel_hi:[1,0]
	v_pk_mul_f32 v[250:251], v[242:243], s[92:93] op_sel_hi:[1,0]
	v_exp_f32_e32 v244, v244
	v_exp_f32_e32 v245, v245
	v_exp_f32_e32 v246, v246
	v_exp_f32_e32 v247, v247
	v_exp_f32_e32 v248, v248
	v_exp_f32_e32 v249, v249
	v_exp_f32_e32 v250, v250
	v_exp_f32_e32 v251, v251
	v_pk_mul_f32 v[236:237], v[236:237], v[6:7]
	v_pk_mul_f32 v[238:239], v[238:239], v[8:9]
	v_pk_mul_f32 v[240:241], v[240:241], v[2:3]
	v_pk_mul_f32 v[242:243], v[242:243], v[4:5]
	v_pk_add_f32 v[244:245], v[244:245], 1.0 op_sel_hi:[1,0]
	v_pk_add_f32 v[246:247], v[246:247], 1.0 op_sel_hi:[1,0]
	v_pk_add_f32 v[248:249], v[248:249], 1.0 op_sel_hi:[1,0]
	v_pk_add_f32 v[250:251], v[250:251], 1.0 op_sel_hi:[1,0]
	v_rcp_f32_e32 v244, v244
	v_rcp_f32_e32 v245, v245
	v_rcp_f32_e32 v246, v246
	v_rcp_f32_e32 v247, v247
	v_rcp_f32_e32 v248, v248
	v_rcp_f32_e32 v249, v249
	v_rcp_f32_e32 v250, v250
	v_rcp_f32_e32 v251, v251
	s_nop 0
	v_pk_mul_f32 v[236:237], v[236:237], v[244:245]
	v_pk_mul_f32 v[238:239], v[238:239], v[246:247]
	v_pk_mul_f32 v[240:241], v[240:241], v[248:249]
	v_pk_mul_f32 v[242:243], v[242:243], v[250:251]
	v_cvt_pk_bf16_f32 v216, v236, v237
	v_cvt_pk_bf16_f32 v217, v238, v239
	v_cvt_pk_bf16_f32 v218, v240, v241
	v_cvt_pk_bf16_f32 v219, v242, v243
	global_store_dwordx4 v[220:221], v[216:219], off sc1
	s_mov_b64 s[66:67], 0x8000
	s_andn2_b64 vcc, exec, s[6:7]
	s_mov_b64 s[6:7], -1
	s_not_b64 s[8:9], s[4:5]
	s_cbranch_vccnz .LBB0_1243
	s_and_b64 vcc, exec, s[8:9]
	s_cbranch_vccnz .LBB0_1242
	s_barrier
	s_branch .LBB0_1242
